# P5 entry: row-scale staging loads issued early, reduction + LDS write moved behind the GEMM prologue's first DMA batch (counted vmcnt), staging no longer serialised in front of the prologue
# speedup vs baseline: 1.0056x; 1.0008x over previous
.LBB0_376:
	v_readlane_b32 s14, v254, 5
	v_cmp_gt_i32_e32 vcc, s85, v234
	v_readlane_b32 s15, v254, 6
	s_and_b64 s[16:17], s[14:15], vcc
	s_and_saveexec_b64 s[14:15], s[16:17]
	s_cbranch_execz .LBB0_378
	s_waitcnt vmcnt(0)
	v_lshl_add_u32 v4, s22, 8, v234
	v_ashrrev_i32_e32 v5, 31, v4
	v_lshlrev_b64 v[4:5], 6, v[4:5]
	s_waitcnt lgkmcnt(0)
	v_lshl_add_u64 v[4:5], s[6:7], 0, v[4:5]
	s_mov_b64 s[16:17], 0x240000
	v_lshl_add_u64 v[16:17], v[4:5], 0, s[16:17]
	v_add_co_u32_e32 v4, vcc, 0x240000, v4
	s_mov_b32 s16, 0x800000
	s_nop 0
	v_addc_co_u32_e32 v5, vcc, 0, v5, vcc
	global_load_dwordx4 v[160:163], v[4:5], off
	s_nop 0
	global_load_dwordx4 v[164:167], v[16:17], off offset:16
	global_load_dwordx4 v[168:171], v[16:17], off offset:48
	s_nop 0
	global_load_dwordx4 v[172:175], v[16:17], off offset:32
.LBB0_378:
	s_or_b64 exec, exec, s[14:15]
	s_waitcnt lgkmcnt(0)
	s_add_u32 s25, s6, 0x4700000
	s_addc_u32 s26, s7, 0
	s_add_u32 s23, s6, 0x1c00000
	s_nop 0
	v_mov_b32_e32 v20, v0
	s_addc_u32 s24, s7, 0
	s_barrier
	s_and_b64 vcc, exec, s[38:39]
	v_readfirstlane_b32 s15, v20
	s_cbranch_vccnz .LBB0_405
	v_lshlrev_b32_e32 v1, 4, v20
	v_add_u32_e32 v2, 0x2000, v1
	v_ashrrev_i32_e32 v4, 31, v2
	v_lshrrev_b32_e32 v4, 22, v4
	v_add_u32_e32 v4, v2, v4
	v_ashrrev_i32_e32 v12, 10, v4
	v_mul_i32_i24_e32 v4, 0x400, v12
	v_sub_u32_e32 v2, v2, v4
	v_lshrrev_b32_e32 v4, 4, v2
	v_bitop3_b32 v2, v4, v2, 32 bitop3:0x6c
	v_ashrrev_i32_e32 v4, 31, v2
	v_lshrrev_b32_e32 v4, 26, v4
	v_add_u32_e32 v4, v2, v4
	v_lshlrev_b32_e32 v5, 3, v12
	v_ashrrev_i32_e32 v13, 6, v4
	v_and_b32_e32 v5, -16, v5
	v_add_u32_e32 v5, v13, v5
	v_and_b32_e32 v6, 3, v13
	s_mov_b32 s17, 0x7fffe0
	v_lshrrev_b32_e32 v7, 2, v5
	v_lshlrev_b32_e32 v8, 1, v5
	v_and_b32_e32 v4, 0xc0, v4
	v_and_or_b32 v6, v5, s17, v6
	v_and_b32_e32 v7, 4, v7
	v_and_b32_e32 v8, 24, v8
	v_sub_u32_e32 v2, v2, v4
	v_or3_b32 v6, v6, v7, v8
	v_lshlrev_b32_e32 v7, 5, v12
	v_ashrrev_i16_sdwa v2, v205, sext(v2) dst_sel:DWORD dst_unused:UNUSED_PAD src0_sel:DWORD src1_sel:BYTE_0
	v_and_b32_e32 v14, 32, v7
	v_bfe_i32 v15, v2, 0, 16
	s_movk_i32 s18, 0x600
	v_mul_u32_u24_e32 v6, 0x600, v6
	v_add_u32_e32 v2, v14, v15
	v_mul_lo_u32 v4, v5, s18
	v_add_lshl_u32 v206, v6, v2, 1
	v_add_lshl_u32 v208, v2, v4, 1
	v_bfe_i32 v2, v20, 27, 1
	v_lshrrev_b32_e32 v2, 22, v2
	v_add_u32_e32 v2, v1, v2
	v_and_b32_e32 v2, 0xfffffc00, v2
	v_sub_u32_e32 v1, v1, v2
	v_lshrrev_b32_e32 v2, 4, v1
	v_ashrrev_i32_e32 v4, 31, v20
	v_bitop3_b32 v1, v2, v1, 32 bitop3:0x6c
	v_lshrrev_b32_e32 v4, 26, v4
	v_ashrrev_i32_e32 v2, 31, v1
	v_add_u32_e32 v4, v20, v4
	v_lshrrev_b32_e32 v2, 26, v2
	v_ashrrev_i32_e32 v17, 6, v4
	v_add_u32_e32 v2, v1, v2
	v_lshlrev_b32_e32 v4, 3, v17
	v_ashrrev_i32_e32 v16, 6, v2
	v_and_b32_e32 v4, -16, v4
	v_add_u32_e32 v4, v16, v4
	v_writelane_b32 v254, s48, 62
	v_and_b32_e32 v5, 3, v16
	v_lshrrev_b32_e32 v6, 2, v4
	v_lshlrev_b32_e32 v7, 1, v4
	v_and_b32_e32 v2, 0xc0, v2
	s_ashr_i32 s16, s15, 6
	v_and_or_b32 v5, v4, s17, v5
	v_and_b32_e32 v6, 4, v6
	v_and_b32_e32 v7, 24, v7
	v_sub_u32_e32 v1, v1, v2
	v_readlane_b32 s19, v254, 17
	s_ashr_i32 s14, s15, 8
	s_lshl_b32 s27, s16, 10
	v_or3_b32 v5, v5, v6, v7
	v_lshlrev_b32_e32 v6, 5, v17
	v_ashrrev_i16_sdwa v1, v205, sext(v1) dst_sel:DWORD dst_unused:UNUSED_PAD src0_sel:DWORD src1_sel:BYTE_0
	s_mul_i32 s17, s19, 0xc0000
	v_and_b32_e32 v18, 32, v6
	v_bfe_i32 v19, v1, 0, 16
	v_mul_lo_u32 v4, v4, s18
	s_add_u32 s18, s23, s17
	s_mul_hi_i32 s17, s19, 0xc0000
	v_mul_u32_u24_e32 v5, 0x600, v5
	v_add_u32_e32 v1, v18, v19
	s_addc_u32 s19, s24, s17
	s_add_i32 s28, s27, 0
	v_add_lshl_u32 v2, v5, v1, 1
	s_add_i32 m0, s28, 0x10000
	v_add_lshl_u32 v210, v1, v4, 1
	global_load_lds_dwordx4 v2, s[18:19]
	s_add_i32 m0, s28, 0x12000
	s_add_u32 s20, s18, 0x60000
	global_load_lds_dwordx4 v206, s[18:19]
	s_addc_u32 s21, s19, 0
	s_add_i32 m0, s28, 0x14000
	v_mov_b32_e32 v207, v3
	global_load_lds_dwordx4 v2, s[20:21]
	s_add_i32 m0, s28, 0x16000
	v_mov_b32_e32 v211, v3
	global_load_lds_dwordx4 v206, s[20:21]
	v_readlane_b32 s20, v254, 13
	s_mov_b32 s30, s20
	s_mul_i32 s17, s20, 0xc0000
	v_readlane_b32 s21, v254, 14
	s_add_u32 s20, s25, s17
	s_mul_hi_i32 s17, s30, 0xc0000
	s_addc_u32 s21, s26, s17
	s_add_i32 s29, s28, 0x2000
	s_mov_b32 m0, s28
	s_add_u32 s34, s20, 0x60000
	global_load_lds_dwordx4 v210, s[20:21]
	s_mov_b32 m0, s29
	s_addc_u32 s35, s21, 0
	s_add_i32 s30, s28, 0x4000
	global_load_lds_dwordx4 v208, s[20:21]
	s_mov_b32 m0, s30
	s_add_i32 s31, s28, 0x6000
	global_load_lds_dwordx4 v210, s[34:35]
	s_mov_b32 m0, s31
	v_mov_b32_e32 v209, v3
	global_load_lds_dwordx4 v208, s[34:35]
	s_cmp_eq_u32 s14, 1
	v_writelane_b32 v255, s49, 0
	v_lshl_add_u64 v[10:11], s[18:19], 0, v[2:3]
	v_lshl_add_u64 v[8:9], s[18:19], 0, v[206:207]
	v_lshl_add_u64 v[4:5], s[20:21], 0, v[210:211]
	s_cselect_b64 s[42:43], -1, 0
	s_cmp_lg_u32 s14, 1
	v_lshl_add_u64 v[6:7], s[20:21], 0, v[208:209]
	s_cbranch_scc1 .LBB0_381
	s_barrier
.LBB0_381:
	v_bfe_u32 v235, v20, 4, 2
	v_and_b32_e32 v1, 15, v20
	v_lshlrev_b32_e32 v21, 4, v235
	v_lshlrev_b32_e32 v20, 2, v20
	s_and_b32 s38, s16, 3
	v_lshl_or_b32 v21, v1, 6, v21
	s_lshl_b32 s16, s14, 13
	v_and_b32_e32 v20, 32, v20
	s_add_i32 m0, s28, 0x18000
	v_lshl_add_u64 v[10:11], v[10:11], 0, s[96:97]
	s_lshl_b32 s34, s14, 6
	v_bitop3_b32 v22, v21, s16, v20 bitop3:0xde
	s_lshl_b32 s35, s38, 5
	s_lshl_b32 s16, s38, 12
	v_readlane_b32 s100, v254, 5
	v_readlane_b32 s101, v254, 6
	v_cmp_gt_i32_e32 vcc, 0x100, v234
	s_nop 1
	s_and_b64 s[100:101], s[100:101], vcc
	s_and_saveexec_b64 s[100:101], s[100:101]
	s_cbranch_execz .Lp5st_skip
	s_waitcnt vmcnt(8)
	v_mov_b32_e32 v176, v160
	v_mov_b32_e32 v177, v172
	v_mov_b32_e32 v172, v161
	v_pk_add_f32 v[160:161], v[176:177], v[172:173]
	v_mov_b32_e32 v172, v162
	v_mov_b32_e32 v173, v174
	v_mov_b32_e32 v174, v163
	v_pk_add_f32 v[162:163], v[172:173], v[174:175]
	s_nop 0
	v_pk_add_f32 v[160:161], v[160:161], v[162:163]
	v_mov_b32_e32 v162, v164
	v_mov_b32_e32 v163, v168
	v_mov_b32_e32 v168, v165
	v_mov_b32_e32 v164, v166
	v_mov_b32_e32 v165, v170
	v_mov_b32_e32 v170, v167
	v_pk_add_f32 v[162:163], v[162:163], v[168:169]
	v_pk_add_f32 v[164:165], v[164:165], v[170:171]
	s_nop 0
	v_pk_add_f32 v[162:163], v[162:163], v[164:165]
	s_nop 0
	v_pk_add_f32 v[160:161], v[160:161], v[162:163]
	s_nop 0
	v_add_f32_e32 v178, v160, v161
	v_fmamk_f32 v178, v178, 0x3a800000, v223
	v_cmp_gt_f32_e32 vcc, 0x800000, v178
	v_mul_f32_e32 v179, 0x4b800000, v178
	s_nop 0
	v_cndmask_b32_e32 v178, v178, v179, vcc
	v_rsq_f32_e32 v178, v178
	s_nop 0
	v_mul_f32_e32 v179, 0x45800000, v178
	v_cndmask_b32_e32 v178, v178, v179, vcc
	v_lshl_add_u32 v179, v234, 2, v225
	ds_write_b32 v179, v178
.Lp5st_skip:
	s_or_b64 exec, exec, s[100:101]
	s_waitcnt vmcnt(2)
	s_barrier
	global_load_lds_dwordx4 v[10:11], off
	v_lshl_add_u64 v[8:9], v[8:9], 0, s[96:97]
	s_add_i32 m0, s28, 0x1a000
	s_add_i32 s36, s28, 0x8000
	s_add_i32 s37, s28, 0xa000
	v_bitop3_b32 v236, v21, s16, v20 bitop3:0xde
	global_load_lds_dwordx4 v[8:9], off
	v_lshl_add_u64 v[4:5], v[4:5], 0, s[96:97]
	s_mov_b32 m0, s36
	s_add_u32 s16, s18, 0x60080
	global_load_lds_dwordx4 v[4:5], off
	v_lshl_add_u64 v[4:5], v[6:7], 0, s[96:97]
	s_mov_b32 m0, s37
	s_addc_u32 s17, s19, 0
	global_load_lds_dwordx4 v[4:5], off
	s_add_i32 m0, s28, 0x1c000
	v_lshl_add_u64 v[4:5], s[16:17], 0, v[2:3]
	global_load_lds_dwordx4 v[4:5], off
	v_lshl_add_u64 v[4:5], s[16:17], 0, v[206:207]
	s_add_i32 m0, s28, 0x1e000
	s_add_u32 s44, s6, 0xb0a0000
	global_load_lds_dwordx4 v[4:5], off
	s_addc_u32 s45, s7, 0
	s_and_b32 s77, s15, 0xffffff00
	s_lshl_b32 s75, s14, 5
	s_lshl_b32 s76, s38, 3
	s_add_i32 s77, s77, 0x20000
	s_cmpk_lt_u32 s15, 0x100
	s_movk_i32 s17, 0x600
	s_cselect_b64 s[46:47], -1, 0
	s_add_u32 s48, s6, 0x7fe0000
	v_lshrrev_b32_e32 v5, 1, v17
	v_mul_lo_u32 v4, v16, s17
	s_movk_i32 s16, 0x6000
	s_addc_u32 s49, s7, 0
	s_lshl_b32 s78, s14, 8
	v_mad_u64_u32 v[4:5], s[14:15], v5, s16, v[4:5]
	v_or_b32_e32 v4, v4, v18
	v_add_lshl_u32 v212, v4, v19, 1
	v_lshrrev_b32_e32 v5, 1, v12
	v_mul_lo_u32 v4, v13, s17
	s_waitcnt vmcnt(6)
	v_mad_u64_u32 v[4:5], s[14:15], v5, s16, v[4:5]
	v_or_b32_e32 v4, v4, v14
	v_readlane_b32 s14, v254, 13
	s_add_i32 s78, s78, 0x20000
	v_mov_b32_e32 v213, v3
	v_add_lshl_u32 v214, v4, v15, 1
	v_mov_b32_e32 v215, v3
	s_mov_b32 s79, 0
	v_add_u32_e32 v237, 0, v22
	v_readlane_b32 s82, v254, 17
	s_mov_b32 s16, s14
	s_barrier
	v_readlane_b32 s15, v254, 14
	s_branch .LBB0_384
